# acquire for the sample rows issued one tile early: the counter load flies under the previous tile, no exposed round trip on the 12-tile / 8-tile workgroups
# baseline (speedup 1.0000x reference)
.LBB0_481:
	s_add_i32 s57, s57, 1
	s_and_b32 s94, s2, 7
	s_cmp_lg_u32 s94, 7
	s_cbranch_scc1 .Lp4_noacq
	s_cmp_lg_u32 s57, 4
	s_cbranch_scc1 .Lp4_chk
	v_readlane_b32 s72, v255, 3
	v_readlane_b32 s73, v255, 4
	v_mov_b32_e32 v250, 0
	s_nop 4
	global_load_dword v251, v250, s[72:73] offset:36 sc1
	s_branch .Lp4_noacq
.Lp4_chk:
	s_cmp_lg_u32 s57, 5
	s_cbranch_scc1 .Lp4_noacq
	s_waitcnt vmcnt(24)
	v_readfirstlane_b32 s94, v251
	s_cmp_ge_u32 s94, 64
	s_cbranch_scc1 .Lp4_acq
	v_readlane_b32 s72, v255, 3
	v_readlane_b32 s73, v255, 4
	v_mov_b32_e32 v250, 0
	s_mov_b32 s95, 0
	s_nop 4

.LBB0_1145:
	s_add_i32 s37, s37, 1
	s_and_b32 s94, s2, 7
	s_cmp_lg_u32 s94, 7
	s_cbranch_scc1 .Lp10_noacq
	s_cmp_lg_u32 s37, 7
	s_cbranch_scc1 .Lp10_chk
	v_readlane_b32 s92, v255, 3
	v_readlane_b32 s93, v255, 4
	v_mov_b32_e32 v226, 0
	s_nop 4
	global_load_dword v227, v226, s[92:93] offset:32 sc1
	s_branch .Lp10_noacq
.Lp10_chk:
	s_cmp_lg_u32 s37, 8
	s_cbranch_scc1 .Lp10_noacq
	s_waitcnt vmcnt(24)
	v_readfirstlane_b32 s94, v227
	s_cmp_ge_u32 s94, 64
	s_cbranch_scc1 .Lp10_acq
	v_readlane_b32 s92, v255, 3
	v_readlane_b32 s93, v255, 4
	v_mov_b32_e32 v226, 0
	s_mov_b32 s95, 0
	s_nop 4
